# combined: prologue rmsnorm loop DPP reductions + hoisted dt-bias load; non-temporal hint on the layer-0 residual base (input x) loads
# speedup vs baseline: 1.0051x; 1.0005x over previous
.LBB0_887:
	v_lshl_add_u32 v182, s26, 8, v169
	v_lshl_or_b32 v180, s51, 8, v192
	v_ashrrev_i32_e32 v183, 31, v182
	v_ashrrev_i32_e32 v181, 31, v180
	v_lshl_add_u64 v[184:185], v[180:181], 2, s[4:5]
	v_lshlrev_b64 v[128:129], 12, v[182:183]
	v_lshl_add_u64 v[128:129], v[184:185], 0, v[128:129]
	global_load_dwordx4 v[198:201], v[128:129], off offset:528 nt
	global_load_dwordx4 v[202:205], v[128:129], off offset:512 nt
	v_lshlrev_b64 v[128:129], 10, v[182:183]
	v_lshl_add_u64 v[188:189], v[128:129], 0, v[180:181]
	v_lshl_add_u64 v[128:129], v[188:189], 2, s[4:5]
	global_load_dwordx4 v[206:209], v[128:129], off nt
	global_load_dwordx4 v[210:213], v[128:129], off offset:16 nt
	v_or_b32_e32 v190, 16, v182
	v_or_b32_e32 v186, 32, v182
	v_ashrrev_i32_e32 v191, 31, v190
	v_ashrrev_i32_e32 v187, 31, v186
	v_lshlrev_b64 v[128:129], 12, v[190:191]
	v_lshlrev_b64 v[130:131], 12, v[186:187]
	v_lshl_add_u64 v[128:129], v[184:185], 0, v[128:129]
	v_lshl_add_u64 v[132:133], v[184:185], 0, v[130:131]
	global_load_dwordx4 v[152:155], v[128:129], off offset:16 nt
	global_load_dwordx4 v[156:159], v[128:129], off nt
	global_load_dwordx4 v[144:147], v[128:129], off offset:528 nt
	global_load_dwordx4 v[148:151], v[128:129], off offset:512 nt
	global_load_dwordx4 v[136:139], v[132:133], off offset:16 nt
	global_load_dwordx4 v[140:143], v[132:133], off nt
	s_nop 0
	global_load_dwordx4 v[128:131], v[132:133], off offset:528 nt
	s_nop 0
	global_load_dwordx4 v[132:135], v[132:133], off offset:512 nt
	v_and_b32_e32 v214, 64, v196
	v_xor_b32_e32 v197, 16, v196
	v_add_u32_e32 v214, 64, v214
	v_cmp_lt_i32_e32 vcc, v197, v214
	v_xor_b32_e32 v215, 32, v196
	v_lshl_add_u64 v[188:189], v[188:189], 1, s[12:13]
	v_cndmask_b32_e32 v197, v196, v197, vcc
	v_lshlrev_b32_e32 v197, 2, v197
	v_cmp_lt_i32_e32 vcc, v215, v214
	s_waitcnt vmcnt(8)
	v_pk_add_f32 v[200:201], v[114:115], v[200:201]
	v_pk_add_f32 v[204:205], v[118:119], v[204:205]
	v_pk_add_f32 v[202:203], v[116:117], v[202:203]
	v_pk_add_f32 v[112:113], v[112:113], v[198:199]
	v_pk_add_f32 v[126:127], v[126:127], v[208:209]
	v_pk_add_f32 v[124:125], v[124:125], v[206:207]
	v_pk_add_f32 v[122:123], v[122:123], v[212:213]
	v_pk_add_f32 v[120:121], v[120:121], v[210:211]
	v_mul_f32_e32 v119, v203, v203
	v_mul_f32_e32 v198, v205, v205
	v_mul_f32_e32 v199, v113, v113
	v_mul_f32_e32 v206, v201, v201
	v_cvt_pk_bf16_f32 v114, v202, v203
	v_cvt_pk_bf16_f32 v115, v204, v205
	v_cvt_pk_bf16_f32 v116, v112, v113
	v_cvt_pk_bf16_f32 v117, v200, v201
	v_mul_f32_e32 v113, v125, v125
	v_mul_f32_e32 v201, v127, v127
	v_mul_f32_e32 v203, v121, v121
	v_mul_f32_e32 v205, v123, v123
	v_fmac_f32_e32 v119, v202, v202
	v_fmac_f32_e32 v198, v204, v204
	v_fmac_f32_e32 v199, v112, v112
	v_fmac_f32_e32 v206, v200, v200
	v_fmac_f32_e32 v113, v124, v124
	v_fmac_f32_e32 v201, v126, v126
	v_fmac_f32_e32 v203, v120, v120
	v_fmac_f32_e32 v205, v122, v122
	v_cvt_pk_bf16_f32 v118, v124, v125
	v_add_f32_e32 v112, v119, v198
	v_add_f32_e32 v119, v199, v206
	v_add_f32_e32 v113, v113, v201
	v_add_f32_e32 v124, v203, v205
	v_add_f32_e32 v112, v112, v119
	v_add_f32_e32 v113, v113, v124
	v_add_f32_e32 v112, v113, v112
	ds_bpermute_b32 v113, v197, v112
	v_cndmask_b32_e32 v216, v196, v215, vcc
	v_lshlrev_b32_e32 v198, 2, v216
	v_cvt_pk_bf16_f32 v119, v126, v127
	v_cvt_pk_bf16_f32 v120, v120, v121
	s_waitcnt lgkmcnt(0)
	v_add_f32_e32 v112, v112, v113
	ds_bpermute_b32 v113, v198, v112
	v_cvt_pk_bf16_f32 v121, v122, v123
	global_store_dwordx4 v[188:189], v[118:121], off sc1
	s_nop 1
	v_lshl_add_u64 v[214:215], v[188:189], 0, s[14:15]
	global_store_dwordx4 v[214:215], v[114:117], off sc1
	s_nop 1
	s_and_saveexec_b64 s[0:1], s[6:7]
	s_cbranch_execz .LBB0_889
	s_waitcnt lgkmcnt(0)
	v_add_f32_e32 v114, v112, v113
	s_lshl_b32 s26, s51, 2
	v_lshlrev_b64 v[112:113], 6, v[182:183]
	s_ashr_i32 s27, s26, 31
	v_lshl_add_u64 v[112:113], s[18:19], 0, v[112:113]
	v_lshl_add_u64 v[112:113], s[26:27], 2, v[112:113]
	s_lshl_b32 s10, s45, 2
	v_lshl_add_u64 v[112:113], v[112:113], 0, s[10:11]
	global_store_dword v[112:113], v114, off
.LBB0_889:
	s_or_b64 exec, exec, s[0:1]
	v_or_b32_e32 v188, 48, v182
	v_ashrrev_i32_e32 v189, 31, v188
	s_waitcnt lgkmcnt(0)
	v_lshlrev_b64 v[112:113], 12, v[188:189]
	v_lshl_add_u64 v[116:117], v[184:185], 0, v[112:113]
	global_load_dwordx4 v[120:123], v[116:117], off offset:16 nt
	global_load_dwordx4 v[124:127], v[116:117], off nt
	global_load_dwordx4 v[112:115], v[116:117], off offset:528 nt
	s_nop 0
	global_load_dwordx4 v[116:119], v[116:117], off offset:512 nt
	s_waitcnt vmcnt(11)
	v_pk_add_f32 v[110:111], v[110:111], v[158:159]
	v_pk_add_f32 v[108:109], v[108:109], v[156:157]
	v_pk_add_f32 v[154:155], v[106:107], v[154:155]
	v_pk_add_f32 v[106:107], v[104:105], v[152:153]
	v_mul_f32_e32 v104, v109, v109
	v_mul_f32_e32 v105, v111, v111
	v_fmac_f32_e32 v104, v108, v108
	v_fmac_f32_e32 v105, v110, v110
	v_add_f32_e32 v104, v104, v105
	v_mul_f32_e32 v105, v107, v107
	v_mul_f32_e32 v152, v155, v155
	v_fmac_f32_e32 v105, v106, v106
	v_fmac_f32_e32 v152, v154, v154
	v_lshlrev_b64 v[200:201], 10, v[190:191]
	v_add_f32_e32 v105, v105, v152
	v_lshl_add_u64 v[200:201], v[200:201], 0, v[180:181]
	v_add_f32_e32 v152, v104, v105
	v_cvt_pk_bf16_f32 v104, v108, v109
	v_cvt_pk_bf16_f32 v105, v110, v111
	v_pk_add_f32 v[102:103], v[102:103], v[150:151]
	v_pk_add_f32 v[100:101], v[100:101], v[148:149]
	v_cvt_pk_bf16_f32 v106, v106, v107
	v_cvt_pk_bf16_f32 v107, v154, v155
	v_lshl_add_u64 v[108:109], v[200:201], 1, s[12:13]
	global_store_dwordx4 v[108:109], v[104:107], off sc1
	s_nop 1
	v_pk_add_f32 v[104:105], v[98:99], v[146:147]
	v_mul_f32_e32 v98, v101, v101
	v_mul_f32_e32 v99, v103, v103
	v_pk_add_f32 v[96:97], v[96:97], v[144:145]
	v_fmac_f32_e32 v98, v100, v100
	v_fmac_f32_e32 v99, v102, v102
	v_add_f32_e32 v98, v98, v99
	v_mul_f32_e32 v99, v97, v97
	v_mul_f32_e32 v106, v105, v105
	v_fmac_f32_e32 v99, v96, v96
	v_fmac_f32_e32 v106, v104, v104
	v_add_f32_e32 v99, v99, v106
	v_add_f32_e32 v98, v98, v99
	v_add_f32_e32 v106, v152, v98
	ds_bpermute_b32 v107, v197, v106
	v_cvt_pk_bf16_f32 v98, v100, v101
	v_cvt_pk_bf16_f32 v100, v96, v97
	v_cvt_pk_bf16_f32 v99, v102, v103
	v_cvt_pk_bf16_f32 v101, v104, v105
	s_waitcnt lgkmcnt(0)
	v_add_f32_e32 v96, v106, v107
	ds_bpermute_b32 v97, v198, v96
	v_lshl_add_u64 v[102:103], v[108:109], 0, s[14:15]
	global_store_dwordx4 v[102:103], v[98:101], off sc1
	s_nop 1
	s_and_saveexec_b64 s[0:1], s[6:7]
	s_cbranch_execz .LBB0_891
	s_waitcnt lgkmcnt(0)
	v_add_f32_e32 v98, v96, v97
	s_lshl_b32 s26, s51, 2
	v_lshlrev_b64 v[96:97], 6, v[190:191]
	s_ashr_i32 s27, s26, 31
	v_lshl_add_u64 v[96:97], s[18:19], 0, v[96:97]
	v_lshl_add_u64 v[96:97], s[26:27], 2, v[96:97]
	s_lshl_b32 s10, s45, 2
	v_lshl_add_u64 v[96:97], v[96:97], 0, s[10:11]
	global_store_dword v[96:97], v98, off
.LBB0_891:
	s_or_b64 exec, exec, s[0:1]
	v_add_u32_e32 v144, 0x80, v182
	v_ashrrev_i32_e32 v145, 31, v144
	s_waitcnt lgkmcnt(0)
	v_lshlrev_b64 v[96:97], 12, v[144:145]
	v_lshl_add_u64 v[100:101], v[184:185], 0, v[96:97]
	global_load_dwordx4 v[104:107], v[100:101], off offset:16 nt
	global_load_dwordx4 v[108:111], v[100:101], off nt
	global_load_dwordx4 v[96:99], v[100:101], off offset:528 nt
	s_nop 0
	global_load_dwordx4 v[100:103], v[100:101], off offset:512 nt
	s_waitcnt vmcnt(14)
	v_pk_add_f32 v[94:95], v[94:95], v[142:143]
	v_pk_add_f32 v[92:93], v[92:93], v[140:141]
	v_pk_add_f32 v[138:139], v[90:91], v[138:139]
	v_pk_add_f32 v[90:91], v[88:89], v[136:137]
	v_mul_f32_e32 v88, v93, v93
	v_mul_f32_e32 v89, v95, v95
	v_fmac_f32_e32 v88, v92, v92
	v_fmac_f32_e32 v89, v94, v94
	v_add_f32_e32 v88, v88, v89
	v_mul_f32_e32 v89, v91, v91
	v_mul_f32_e32 v136, v139, v139
	v_fmac_f32_e32 v89, v90, v90
	v_fmac_f32_e32 v136, v138, v138
	v_lshlrev_b64 v[146:147], 10, v[186:187]
	v_add_f32_e32 v89, v89, v136
	v_lshl_add_u64 v[146:147], v[146:147], 0, v[180:181]
	v_add_f32_e32 v136, v88, v89
	v_cvt_pk_bf16_f32 v88, v92, v93
	v_cvt_pk_bf16_f32 v89, v94, v95
	v_pk_add_f32 v[86:87], v[86:87], v[134:135]
	v_pk_add_f32 v[84:85], v[84:85], v[132:133]
	v_cvt_pk_bf16_f32 v90, v90, v91
	v_cvt_pk_bf16_f32 v91, v138, v139
	v_lshl_add_u64 v[92:93], v[146:147], 1, s[12:13]
	global_store_dwordx4 v[92:93], v[88:91], off sc1
	s_nop 1
	v_pk_add_f32 v[88:89], v[82:83], v[130:131]
	v_mul_f32_e32 v82, v85, v85
	v_mul_f32_e32 v83, v87, v87
	v_pk_add_f32 v[80:81], v[80:81], v[128:129]
	v_fmac_f32_e32 v82, v84, v84
	v_fmac_f32_e32 v83, v86, v86
	v_add_f32_e32 v82, v82, v83
	v_mul_f32_e32 v83, v81, v81
	v_mul_f32_e32 v90, v89, v89
	v_fmac_f32_e32 v83, v80, v80
	v_fmac_f32_e32 v90, v88, v88
	v_add_f32_e32 v83, v83, v90
	v_add_f32_e32 v82, v82, v83
	v_add_f32_e32 v90, v136, v82
	ds_bpermute_b32 v91, v197, v90
	v_cvt_pk_bf16_f32 v82, v84, v85
	v_cvt_pk_bf16_f32 v84, v80, v81
	v_cvt_pk_bf16_f32 v83, v86, v87
	v_cvt_pk_bf16_f32 v85, v88, v89
	s_waitcnt lgkmcnt(0)
	v_add_f32_e32 v80, v90, v91
	ds_bpermute_b32 v81, v198, v80
	v_lshl_add_u64 v[86:87], v[92:93], 0, s[14:15]
	global_store_dwordx4 v[86:87], v[82:85], off sc1
	s_nop 1
	s_and_saveexec_b64 s[0:1], s[6:7]
	s_cbranch_execz .LBB0_893
	s_waitcnt lgkmcnt(0)
	v_add_f32_e32 v82, v80, v81
	s_lshl_b32 s26, s51, 2
	v_lshlrev_b64 v[80:81], 6, v[186:187]
	s_ashr_i32 s27, s26, 31
	v_lshl_add_u64 v[80:81], s[18:19], 0, v[80:81]
	v_lshl_add_u64 v[80:81], s[26:27], 2, v[80:81]
	s_lshl_b32 s10, s45, 2
	v_lshl_add_u64 v[80:81], v[80:81], 0, s[10:11]
	global_store_dword v[80:81], v82, off
.LBB0_893:
	s_or_b64 exec, exec, s[0:1]
	v_add_u32_e32 v128, 0x90, v182
	v_ashrrev_i32_e32 v129, 31, v128
	s_waitcnt lgkmcnt(0)
	v_lshlrev_b64 v[80:81], 12, v[128:129]
	v_lshl_add_u64 v[84:85], v[184:185], 0, v[80:81]
	global_load_dwordx4 v[88:91], v[84:85], off offset:16 nt
	global_load_dwordx4 v[92:95], v[84:85], off nt
	global_load_dwordx4 v[80:83], v[84:85], off offset:528 nt
	s_nop 0
	global_load_dwordx4 v[84:87], v[84:85], off offset:512 nt
	s_waitcnt vmcnt(14)
	v_pk_add_f32 v[78:79], v[78:79], v[126:127]
	v_pk_add_f32 v[76:77], v[76:77], v[124:125]
	v_pk_add_f32 v[122:123], v[74:75], v[122:123]
	v_pk_add_f32 v[74:75], v[72:73], v[120:121]
	v_mul_f32_e32 v72, v77, v77
	v_mul_f32_e32 v73, v79, v79
	v_fmac_f32_e32 v72, v76, v76
	v_fmac_f32_e32 v73, v78, v78
	v_add_f32_e32 v72, v72, v73
	v_mul_f32_e32 v73, v75, v75
	v_mul_f32_e32 v120, v123, v123
	v_fmac_f32_e32 v73, v74, v74
	v_fmac_f32_e32 v120, v122, v122
	v_lshlrev_b64 v[130:131], 10, v[188:189]
	v_add_f32_e32 v73, v73, v120
	v_lshl_add_u64 v[130:131], v[130:131], 0, v[180:181]
	v_add_f32_e32 v120, v72, v73
	v_cvt_pk_bf16_f32 v72, v76, v77
	v_cvt_pk_bf16_f32 v73, v78, v79
	s_waitcnt vmcnt(14)
	v_pk_add_f32 v[70:71], v[70:71], v[118:119]
	v_pk_add_f32 v[68:69], v[68:69], v[116:117]
	v_cvt_pk_bf16_f32 v74, v74, v75
	v_cvt_pk_bf16_f32 v75, v122, v123
	v_lshl_add_u64 v[76:77], v[130:131], 1, s[12:13]
	global_store_dwordx4 v[76:77], v[72:75], off sc1
	s_nop 1
	v_pk_add_f32 v[72:73], v[66:67], v[114:115]
	v_mul_f32_e32 v66, v69, v69
	v_mul_f32_e32 v67, v71, v71
	v_pk_add_f32 v[64:65], v[64:65], v[112:113]
	v_fmac_f32_e32 v66, v68, v68
	v_fmac_f32_e32 v67, v70, v70
	v_add_f32_e32 v66, v66, v67
	v_mul_f32_e32 v67, v65, v65
	v_mul_f32_e32 v74, v73, v73
	v_fmac_f32_e32 v67, v64, v64
	v_fmac_f32_e32 v74, v72, v72
	v_add_f32_e32 v67, v67, v74
	v_add_f32_e32 v66, v66, v67
	v_add_f32_e32 v74, v120, v66
	ds_bpermute_b32 v75, v197, v74
	v_cvt_pk_bf16_f32 v66, v68, v69
	v_cvt_pk_bf16_f32 v68, v64, v65
	v_cvt_pk_bf16_f32 v67, v70, v71
	v_cvt_pk_bf16_f32 v69, v72, v73
	s_waitcnt lgkmcnt(0)
	v_add_f32_e32 v64, v74, v75
	ds_bpermute_b32 v65, v198, v64
	v_lshl_add_u64 v[70:71], v[76:77], 0, s[14:15]
	global_store_dwordx4 v[70:71], v[66:69], off sc1
	s_nop 1
	s_and_saveexec_b64 s[0:1], s[6:7]
	s_cbranch_execz .LBB0_895
	s_waitcnt lgkmcnt(0)
	v_add_f32_e32 v66, v64, v65
	s_lshl_b32 s26, s51, 2
	v_lshlrev_b64 v[64:65], 6, v[188:189]
	s_ashr_i32 s27, s26, 31
	v_lshl_add_u64 v[64:65], s[18:19], 0, v[64:65]
	v_lshl_add_u64 v[64:65], s[26:27], 2, v[64:65]
	s_lshl_b32 s10, s45, 2
	v_lshl_add_u64 v[64:65], v[64:65], 0, s[10:11]
	global_store_dword v[64:65], v66, off
.LBB0_895:
	s_or_b64 exec, exec, s[0:1]
	v_add_u32_e32 v112, 0xa0, v182
	v_ashrrev_i32_e32 v113, 31, v112
	s_waitcnt lgkmcnt(0)
	v_lshlrev_b64 v[64:65], 12, v[112:113]
	v_lshl_add_u64 v[68:69], v[184:185], 0, v[64:65]
	global_load_dwordx4 v[72:75], v[68:69], off offset:16 nt
	global_load_dwordx4 v[76:79], v[68:69], off nt
	global_load_dwordx4 v[64:67], v[68:69], off offset:528 nt
	s_nop 0
	global_load_dwordx4 v[68:71], v[68:69], off offset:512 nt
	s_waitcnt vmcnt(14)
	v_pk_add_f32 v[62:63], v[62:63], v[110:111]
	v_pk_add_f32 v[60:61], v[60:61], v[108:109]
	v_pk_add_f32 v[106:107], v[58:59], v[106:107]
	v_pk_add_f32 v[58:59], v[56:57], v[104:105]
	v_mul_f32_e32 v56, v61, v61
	v_mul_f32_e32 v57, v63, v63
	v_fmac_f32_e32 v56, v60, v60
	v_fmac_f32_e32 v57, v62, v62
	v_add_f32_e32 v56, v56, v57
	v_mul_f32_e32 v57, v59, v59
	v_mul_f32_e32 v104, v107, v107
	v_fmac_f32_e32 v57, v58, v58
	v_fmac_f32_e32 v104, v106, v106
	v_lshlrev_b64 v[114:115], 10, v[144:145]
	v_add_f32_e32 v57, v57, v104
	v_lshl_add_u64 v[114:115], v[114:115], 0, v[180:181]
	v_add_f32_e32 v104, v56, v57
	v_cvt_pk_bf16_f32 v56, v60, v61
	v_cvt_pk_bf16_f32 v57, v62, v63
	s_waitcnt vmcnt(14)
	v_pk_add_f32 v[54:55], v[54:55], v[102:103]
	v_pk_add_f32 v[52:53], v[52:53], v[100:101]
	v_cvt_pk_bf16_f32 v58, v58, v59
	v_cvt_pk_bf16_f32 v59, v106, v107
	v_lshl_add_u64 v[60:61], v[114:115], 1, s[12:13]
	global_store_dwordx4 v[60:61], v[56:59], off sc1
	s_nop 1
	v_pk_add_f32 v[56:57], v[50:51], v[98:99]
	v_mul_f32_e32 v50, v53, v53
	v_mul_f32_e32 v51, v55, v55
	v_pk_add_f32 v[48:49], v[48:49], v[96:97]
	v_fmac_f32_e32 v50, v52, v52
	v_fmac_f32_e32 v51, v54, v54
	v_add_f32_e32 v50, v50, v51
	v_mul_f32_e32 v51, v49, v49
	v_mul_f32_e32 v58, v57, v57
	v_fmac_f32_e32 v51, v48, v48
	v_fmac_f32_e32 v58, v56, v56
	v_add_f32_e32 v51, v51, v58
	v_add_f32_e32 v50, v50, v51
	v_add_f32_e32 v58, v104, v50
	ds_bpermute_b32 v59, v197, v58
	v_cvt_pk_bf16_f32 v50, v52, v53
	v_cvt_pk_bf16_f32 v52, v48, v49
	v_cvt_pk_bf16_f32 v51, v54, v55
	v_cvt_pk_bf16_f32 v53, v56, v57
	s_waitcnt lgkmcnt(0)
	v_add_f32_e32 v48, v58, v59
	ds_bpermute_b32 v49, v198, v48
	v_lshl_add_u64 v[54:55], v[60:61], 0, s[14:15]
	global_store_dwordx4 v[54:55], v[50:53], off sc1
	s_nop 1
	s_and_saveexec_b64 s[0:1], s[6:7]
	s_cbranch_execz .LBB0_897
	s_waitcnt lgkmcnt(0)
	v_add_f32_e32 v50, v48, v49
	s_lshl_b32 s26, s51, 2
	v_lshlrev_b64 v[48:49], 6, v[144:145]
	s_ashr_i32 s27, s26, 31
	v_lshl_add_u64 v[48:49], s[18:19], 0, v[48:49]
	v_lshl_add_u64 v[48:49], s[26:27], 2, v[48:49]
	s_lshl_b32 s10, s45, 2
	v_lshl_add_u64 v[48:49], v[48:49], 0, s[10:11]
	global_store_dword v[48:49], v50, off
.LBB0_897:
	s_or_b64 exec, exec, s[0:1]
	v_add_u32_e32 v96, 0xb0, v182
	v_ashrrev_i32_e32 v97, 31, v96
	s_waitcnt lgkmcnt(0)
	v_lshlrev_b64 v[48:49], 12, v[96:97]
	v_lshl_add_u64 v[52:53], v[184:185], 0, v[48:49]
	global_load_dwordx4 v[56:59], v[52:53], off offset:16 nt
	global_load_dwordx4 v[60:63], v[52:53], off nt
	global_load_dwordx4 v[48:51], v[52:53], off offset:528 nt
	s_nop 0
	global_load_dwordx4 v[52:55], v[52:53], off offset:512 nt
	s_waitcnt vmcnt(14)
	v_pk_add_f32 v[46:47], v[46:47], v[94:95]
	v_pk_add_f32 v[44:45], v[44:45], v[92:93]
	v_pk_add_f32 v[90:91], v[42:43], v[90:91]
	v_pk_add_f32 v[42:43], v[40:41], v[88:89]
	v_mul_f32_e32 v40, v45, v45
	v_mul_f32_e32 v41, v47, v47
	v_fmac_f32_e32 v40, v44, v44
	v_fmac_f32_e32 v41, v46, v46
	v_add_f32_e32 v40, v40, v41
	v_mul_f32_e32 v41, v43, v43
	v_mul_f32_e32 v88, v91, v91
	v_fmac_f32_e32 v41, v42, v42
	v_fmac_f32_e32 v88, v90, v90
	v_lshlrev_b64 v[98:99], 10, v[128:129]
	v_add_f32_e32 v41, v41, v88
	v_lshl_add_u64 v[98:99], v[98:99], 0, v[180:181]
	v_add_f32_e32 v88, v40, v41
	v_cvt_pk_bf16_f32 v40, v44, v45
	v_cvt_pk_bf16_f32 v41, v46, v47
	s_waitcnt vmcnt(14)
	v_pk_add_f32 v[38:39], v[38:39], v[86:87]
	v_pk_add_f32 v[36:37], v[36:37], v[84:85]
	v_cvt_pk_bf16_f32 v42, v42, v43
	v_cvt_pk_bf16_f32 v43, v90, v91
	v_lshl_add_u64 v[44:45], v[98:99], 1, s[12:13]
	global_store_dwordx4 v[44:45], v[40:43], off sc1
	s_nop 1
	v_pk_add_f32 v[40:41], v[34:35], v[82:83]
	v_mul_f32_e32 v34, v37, v37
	v_mul_f32_e32 v35, v39, v39
	v_pk_add_f32 v[32:33], v[32:33], v[80:81]
	v_fmac_f32_e32 v34, v36, v36
	v_fmac_f32_e32 v35, v38, v38
	v_add_f32_e32 v34, v34, v35
	v_mul_f32_e32 v35, v33, v33
	v_mul_f32_e32 v42, v41, v41
	v_fmac_f32_e32 v35, v32, v32
	v_fmac_f32_e32 v42, v40, v40
	v_add_f32_e32 v35, v35, v42
	v_add_f32_e32 v34, v34, v35
	v_add_f32_e32 v42, v88, v34
	ds_bpermute_b32 v43, v197, v42
	v_cvt_pk_bf16_f32 v34, v36, v37
	v_cvt_pk_bf16_f32 v36, v32, v33
	v_cvt_pk_bf16_f32 v35, v38, v39
	v_cvt_pk_bf16_f32 v37, v40, v41
	s_waitcnt lgkmcnt(0)
	v_add_f32_e32 v32, v42, v43
	ds_bpermute_b32 v33, v198, v32
	v_lshl_add_u64 v[38:39], v[44:45], 0, s[14:15]
	global_store_dwordx4 v[38:39], v[34:37], off sc1
	s_nop 1
	s_and_saveexec_b64 s[0:1], s[6:7]
	s_cbranch_execz .LBB0_899
	s_waitcnt lgkmcnt(0)
	v_add_f32_e32 v34, v32, v33
	s_lshl_b32 s26, s51, 2
	v_lshlrev_b64 v[32:33], 6, v[128:129]
	s_ashr_i32 s27, s26, 31
	v_lshl_add_u64 v[32:33], s[18:19], 0, v[32:33]
	v_lshl_add_u64 v[32:33], s[26:27], 2, v[32:33]
	s_lshl_b32 s10, s45, 2
	v_lshl_add_u64 v[32:33], v[32:33], 0, s[10:11]
	global_store_dword v[32:33], v34, off
